# attention main loops: K fragments of QK(t+1) read 4+ MFMA groups ahead into spare register quads, lgkmcnt waits re-derived (on top of v24)
# speedup vs baseline: 1.0040x; 1.0040x over previous
.LBB0_789:
	s_mul_hi_u32 s4, s61, 0xaaaaaaab
	s_lshr_b32 s50, s4, 1
	s_mul_i32 s4, s50, 0xffffa000
	s_add_i32 s4, s14, s4
	s_and_b32 s51, s14, 0x6000
	v_add_u32_e32 v217, s4, v214
	v_add_u32_e32 v216, s51, v147
	v_add_u32_e32 v114, 0xffffc000, v217
	v_add_u32_e32 v252, 0xffffc000, v217
	ds_read_b64_tr_b16 v[118:119], v216 offset:24576
	ds_read_b64_tr_b16 v[120:121], v216 offset:25088
	ds_read_b64_tr_b16 v[122:123], v216 offset:28672
	ds_read_b64_tr_b16 v[124:125], v216 offset:29184
	ds_read_b128 v[114:117], v114
	ds_read_b128 v[236:239], v252 offset:512
	ds_read_b128 v[240:243], v252 offset:2048
	ds_read_b128 v[244:247], v252 offset:2560
	ds_read_b128 v[248:251], v252 offset:4096
	s_waitcnt lgkmcnt(7)
	v_mfma_f32_32x32x16_bf16 v[18:33], v[164:167], v[118:121], v[18:33]
	ds_read_b64_tr_b16 v[126:127], v216 offset:57344
	ds_read_b64_tr_b16 v[128:129], v216 offset:57856
	s_waitcnt lgkmcnt(7)
	v_mfma_f32_32x32x16_bf16 v[50:65], v[164:167], v[122:125], v[50:65]
	ds_read_b64_tr_b16 v[130:131], v216 offset:61440
	ds_read_b64_tr_b16 v[132:133], v216 offset:61952
	s_waitcnt lgkmcnt(2)
	v_mfma_f32_32x32x16_bf16 v[34:49], v[164:167], v[126:129], v[34:49]
	ds_read_b64_tr_b16 v[118:119], v216 offset:25600
	ds_read_b64_tr_b16 v[120:121], v216 offset:26112
	s_waitcnt lgkmcnt(2)
	v_mfma_f32_32x32x16_bf16 v[2:17], v[164:167], v[130:133], v[2:17]
	ds_read_b64_tr_b16 v[180:181], v216 offset:29696
	ds_read_b64_tr_b16 v[182:183], v216 offset:30208
	v_max_f32_e32 v122, v99, v99
	v_max_f32_e32 v123, v98, v98
	v_max_f32_e32 v122, v123, v122
	v_max3_f32 v123, v100, v101, v67
	v_max3_f32 v122, v122, v66, v68
	v_max3_f32 v122, v122, v69, v102
	v_max3_f32 v123, v123, v104, v105
	v_max3_f32 v122, v122, v103, v70
	v_max3_f32 v123, v123, v72, v73
	v_max3_f32 v122, v122, v71, v106
	v_max3_f32 v123, v123, v108, v109
	v_max3_f32 v122, v122, v107, v74
	v_max3_f32 v123, v123, v76, v77
	v_max3_f32 v122, v122, v75, v110
	v_max3_f32 v123, v123, v112, v113
	v_max3_f32 v122, v122, v111, v78
	v_max3_f32 v123, v123, v80, v81
	v_max3_f32 v122, v122, v79, v123
	v_mov_b32_e32 v123, v122
	s_nop 1
	v_permlane32_swap_b32_e32 v122, v123
	v_max_f32_e32 v123, v123, v123
	v_max_f32_e32 v122, v122, v122
	v_max_f32_e32 v122, v122, v123
	v_cmp_lt_f32_e32 vcc, s15, v122
	s_cmp_lg_u64 vcc, 0
	s_cselect_b64 s[4:5], -1, 0
	s_cbranch_vccz .LBB0_793
	v_max_f32_e32 v82, v122, v122
	v_max_f32_e32 v122, 0, v82
	v_exp_f32_e64 v123, -v122
	v_add_f32_e32 v212, v212, v122
	v_xor_b32_e32 v82, 0x80000000, v212
	v_mov_b32_e32 v83, v82
	v_mov_b32_e32 v84, v82
	v_mov_b32_e32 v85, v82
	v_mov_b32_e32 v86, v82
	v_mov_b32_e32 v87, v82
	v_mov_b32_e32 v88, v82
	v_mov_b32_e32 v89, v82
	v_mov_b32_e32 v90, v82
	v_mov_b32_e32 v91, v82
	v_mov_b32_e32 v92, v82
	v_mov_b32_e32 v93, v82
	v_mov_b32_e32 v94, v82
	v_mov_b32_e32 v95, v82
	v_mov_b32_e32 v96, v82
	v_mov_b32_e32 v97, v82
	s_and_saveexec_b64 vcc, s[8:9]
	ds_write_b32 v1, v123
	s_or_b64 exec, exec, vcc
	v_sub_f32_e32 v113, v113, v122
	v_sub_f32_e32 v112, v112, v122
	v_sub_f32_e32 v111, v111, v122
	v_sub_f32_e32 v110, v110, v122
	v_sub_f32_e32 v109, v109, v122
	v_sub_f32_e32 v108, v108, v122
	v_sub_f32_e32 v107, v107, v122
	v_sub_f32_e32 v106, v106, v122
	v_sub_f32_e32 v105, v105, v122
	v_sub_f32_e32 v104, v104, v122
	v_sub_f32_e32 v103, v103, v122
	v_sub_f32_e32 v102, v102, v122
	v_sub_f32_e32 v101, v101, v122
	v_sub_f32_e32 v100, v100, v122
	v_sub_f32_e32 v99, v99, v122
	v_sub_f32_e32 v98, v98, v122
	v_sub_f32_e32 v81, v81, v122
	v_sub_f32_e32 v80, v80, v122
	v_sub_f32_e32 v79, v79, v122
	v_sub_f32_e32 v78, v78, v122
	v_sub_f32_e32 v77, v77, v122
	v_sub_f32_e32 v76, v76, v122
	v_sub_f32_e32 v75, v75, v122
	v_sub_f32_e32 v74, v74, v122
	v_sub_f32_e32 v73, v73, v122
	v_sub_f32_e32 v72, v72, v122
	v_sub_f32_e32 v71, v71, v122
	v_sub_f32_e32 v70, v70, v122
	v_sub_f32_e32 v69, v69, v122
	v_sub_f32_e32 v68, v68, v122
	v_sub_f32_e32 v67, v67, v122
	v_sub_f32_e32 v66, v66, v122
	v_mul_f32_e32 v213, v213, v123
.LBB0_793:
	v_exp_f32_e32 v164, v98
	v_mfma_f32_32x32x16_bf16 v[130:145], v[114:117], v[148:151], v[82:97]
	v_exp_f32_e32 v165, v99
	v_exp_f32_e32 v230, v100
	ds_read_b64_tr_b16 v[218:219], v216 offset:58368
	ds_read_b64_tr_b16 v[220:221], v216 offset:58880
	v_exp_f32_e32 v231, v101
	v_add_f32_e32 v98, 0, v164
	s_waitcnt lgkmcnt(4)
	v_mfma_f32_32x32x16_bf16 v[18:33], v[168:171], v[118:121], v[18:33]
	v_add_f32_e32 v98, v165, v98
	v_add_f32_e32 v98, v230, v98
	v_add_f32_e32 v232, v231, v98
	ds_read_b64_tr_b16 v[98:99], v216 offset:62464
	ds_read_b64_tr_b16 v[100:101], v216 offset:62976
	v_exp_f32_e32 v233, v102
	v_mfma_f32_32x32x16_bf16 v[114:129], v[236:239], v[148:151], v[82:97]
	ds_read_b128 v[236:239], v252 offset:4608
	v_exp_f32_e32 v222, v103
	v_exp_f32_e32 v223, v104
	v_exp_f32_e32 v224, v105
	v_add_f32_e32 v102, v233, v232
	v_add_f32_e32 v102, v222, v102
	v_add_f32_e32 v102, v223, v102
	v_add_f32_e32 v225, v224, v102
	s_waitcnt lgkmcnt(5)
	v_mfma_f32_32x32x16_bf16 v[50:65], v[168:171], v[180:183], v[50:65]
	v_exp_f32_e32 v232, v106
	v_mfma_f32_32x32x16_bf16 v[130:145], v[240:243], v[152:155], v[130:145]
	ds_read_b128 v[240:243], v252 offset:6144
	v_exp_f32_e32 v234, v107
	v_exp_f32_e32 v226, v108
	ds_read_b64_tr_b16 v[102:103], v216 offset:26624
	ds_read_b64_tr_b16 v[104:105], v216 offset:27136
	v_exp_f32_e32 v227, v109
	v_add_f32_e32 v106, v232, v225
	s_waitcnt lgkmcnt(6)
	v_mfma_f32_32x32x16_bf16 v[34:49], v[168:171], v[218:221], v[34:49]
	v_add_f32_e32 v106, v234, v106
	v_add_f32_e32 v106, v226, v106
	v_add_f32_e32 v225, v227, v106
	v_cvt_pk_bf16_f32 v164, v164, v165
	v_cvt_pk_bf16_f32 v165, v230, v231
	v_exp_f32_e32 v228, v110
	v_mfma_f32_32x32x16_bf16 v[114:129], v[244:247], v[152:155], v[114:129]
	ds_read_b128 v[244:247], v252 offset:6656
	v_exp_f32_e32 v229, v111
	v_exp_f32_e32 v180, v112
	ds_read_b64_tr_b16 v[106:107], v216 offset:30720
	ds_read_b64_tr_b16 v[108:109], v216 offset:31232
	v_exp_f32_e32 v181, v113
	v_add_f32_e32 v110, v228, v225
	s_waitcnt lgkmcnt(7)
	v_mfma_f32_32x32x16_bf16 v[2:17], v[168:171], v[98:101], v[2:17]
	v_add_f32_e32 v110, v229, v110
	v_add_f32_e32 v110, v180, v110
	v_add_f32_e32 v182, v181, v110
	v_cvt_pk_bf16_f32 v166, v233, v222
	v_cvt_pk_bf16_f32 v167, v223, v224
	v_mfma_f32_32x32x16_bf16 v[130:145], v[248:251], v[156:159], v[130:145]
	v_exp_f32_e32 v183, v66
	ds_read_b64_tr_b16 v[98:99], v216 offset:59392
	ds_read_b64_tr_b16 v[100:101], v216 offset:59904
	v_exp_f32_e32 v222, v67
	v_add_f32_e32 v66, v183, v182
	v_cvt_pk_bf16_f32 v168, v232, v234
	s_waitcnt lgkmcnt(5)
	v_mfma_f32_32x32x16_bf16 v[18:33], v[172:175], v[102:105], v[18:33]
	v_add_f32_e32 v66, v222, v66
	v_cvt_pk_bf16_f32 v169, v226, v227
	s_waitcnt lgkmcnt(2)
	v_mfma_f32_32x32x16_bf16 v[50:65], v[172:175], v[106:109], v[50:65]
	v_exp_f32_e32 v182, v68
	ds_read_b64_tr_b16 v[102:103], v216 offset:63488
	ds_read_b64_tr_b16 v[104:105], v216 offset:64000
	v_exp_f32_e32 v218, v69
	v_cvt_pk_bf16_f32 v170, v228, v229
	v_add_f32_e32 v66, v182, v66
	v_cvt_pk_bf16_f32 v171, v180, v181
	v_add_f32_e32 v219, v218, v66
	v_mfma_f32_32x32x16_bf16 v[114:129], v[236:239], v[156:159], v[114:129]
	v_exp_f32_e32 v110, v70
	ds_read_b64_tr_b16 v[66:67], v216 offset:27648
	ds_read_b64_tr_b16 v[68:69], v216 offset:28160
	v_exp_f32_e32 v111, v71
	v_add_f32_e32 v70, v110, v219
	v_add_f32_e32 v70, v111, v70
	s_waitcnt lgkmcnt(4)
	v_mfma_f32_32x32x16_bf16 v[34:49], v[172:175], v[98:101], v[34:49]
	s_waitcnt lgkmcnt(2)
	v_mfma_f32_32x32x16_bf16 v[2:17], v[172:175], v[102:105], v[2:17]
	v_exp_f32_e32 v112, v72
	ds_read_b64_tr_b16 v[98:99], v216 offset:31744
	ds_read_b64_tr_b16 v[100:101], v216 offset:32256
	v_exp_f32_e32 v113, v73
	v_add_f32_e32 v70, v112, v70
	v_add_f32_e32 v172, v113, v70
	v_mfma_f32_32x32x16_bf16 v[130:145], v[240:243], v[160:163], v[130:145]
	v_exp_f32_e32 v74, v74
	ds_read_b64_tr_b16 v[70:71], v216 offset:60416
	ds_read_b64_tr_b16 v[72:73], v216 offset:60928
	v_exp_f32_e32 v75, v75
	v_add_f32_e32 v106, v74, v172
	v_cvt_pk_bf16_f32 v172, v183, v222
	s_waitcnt lgkmcnt(4)
	v_mfma_f32_32x32x16_bf16 v[18:33], v[176:179], v[66:69], v[18:33]
	v_add_f32_e32 v106, v75, v106
	v_cvt_pk_bf16_f32 v173, v182, v218
	s_waitcnt lgkmcnt(2)
	v_mfma_f32_32x32x16_bf16 v[50:65], v[176:179], v[98:101], v[50:65]
	v_exp_f32_e32 v76, v76
	v_exp_f32_e32 v77, v77
	ds_read_b64_tr_b16 v[66:67], v216 offset:64512
	ds_read_b64_tr_b16 v[68:69], v216 offset:65024
	v_cvt_pk_bf16_f32 v174, v110, v111
	v_add_f32_e32 v106, v76, v106
	v_add_f32_e32 v106, v77, v106
	v_cvt_pk_bf16_f32 v175, v112, v113
	v_mfma_f32_32x32x16_bf16 v[114:129], v[244:247], v[160:163], v[114:129]
	v_exp_f32_e32 v78, v78
	v_exp_f32_e32 v79, v79
	v_add_f32_e32 v98, v78, v106
	v_add_f32_e32 v98, v79, v98
	s_waitcnt lgkmcnt(2)
	v_mfma_f32_32x32x16_bf16 v[34:49], v[176:179], v[70:73], v[34:49]
	s_waitcnt lgkmcnt(0)
	v_mfma_f32_32x32x16_bf16 v[2:17], v[176:179], v[66:69], v[2:17]
	v_exp_f32_e32 v80, v80
	v_exp_f32_e32 v81, v81
	v_add_f32_e32 v66, v80, v98
	v_add_f32_e32 v66, v81, v66
	s_andn2_b64 vcc, exec, s[4:5]
	s_cbranch_vccnz .LBB0_795
	s_waitcnt lgkmcnt(0)
	ds_read_b128 v[68:71], v215 offset:96
	ds_read_b128 v[98:101], v215 offset:64
	ds_read_b128 v[102:105], v215 offset:32
	ds_read_b128 v[106:109], v215
	s_waitcnt lgkmcnt(0)
	v_pk_mul_f32 v[30:31], v[30:31], v[68:69]
	v_pk_mul_f32 v[26:27], v[26:27], v[98:99]
	v_pk_mul_f32 v[22:23], v[22:23], v[102:103]
	v_pk_mul_f32 v[32:33], v[32:33], v[70:71]
	v_pk_mul_f32 v[28:29], v[28:29], v[100:101]
	v_pk_mul_f32 v[24:25], v[24:25], v[104:105]
	v_pk_mul_f32 v[20:21], v[20:21], v[108:109]
	v_pk_mul_f32 v[18:19], v[18:19], v[106:107]
	v_pk_mul_f32 v[62:63], v[62:63], v[68:69]
	v_pk_mul_f32 v[58:59], v[58:59], v[98:99]
	v_pk_mul_f32 v[54:55], v[54:55], v[102:103]
	v_pk_mul_f32 v[64:65], v[64:65], v[70:71]
	v_pk_mul_f32 v[60:61], v[60:61], v[100:101]
	v_pk_mul_f32 v[56:57], v[56:57], v[104:105]
	v_pk_mul_f32 v[52:53], v[52:53], v[108:109]
	v_pk_mul_f32 v[50:51], v[50:51], v[106:107]
	v_pk_mul_f32 v[46:47], v[46:47], v[68:69]
	v_pk_mul_f32 v[42:43], v[42:43], v[98:99]
	v_pk_mul_f32 v[38:39], v[38:39], v[102:103]
	v_pk_mul_f32 v[48:49], v[48:49], v[70:71]
	v_pk_mul_f32 v[44:45], v[44:45], v[100:101]
	v_pk_mul_f32 v[40:41], v[40:41], v[104:105]
	v_pk_mul_f32 v[36:37], v[36:37], v[108:109]
	v_pk_mul_f32 v[34:35], v[34:35], v[106:107]
	v_pk_mul_f32 v[14:15], v[14:15], v[68:69]
	v_pk_mul_f32 v[10:11], v[10:11], v[98:99]
	v_pk_mul_f32 v[6:7], v[6:7], v[102:103]
	v_pk_mul_f32 v[16:17], v[16:17], v[70:71]
	v_pk_mul_f32 v[12:13], v[12:13], v[100:101]
	v_pk_mul_f32 v[8:9], v[8:9], v[104:105]
	v_pk_mul_f32 v[4:5], v[4:5], v[108:109]
	v_pk_mul_f32 v[2:3], v[2:3], v[106:107]

.LBB0_802:
	s_mul_hi_u32 s4, s30, 0xaaaaaaab
	s_lshr_b32 s4, s4, 1
	s_mulk_i32 s4, 0xa000
	s_add_i32 s5, s14, 0xffffa000
	s_add_i32 s4, s14, s4
	s_and_b32 s5, s5, 0x6000
	v_add_u32_e32 v194, s4, v214
	v_add_f32_e32 v192, v213, v66
	v_add_u32_e32 v193, s5, v147
	v_add_u32_e32 v66, 0xffffe000, v194
	v_add_u32_e32 v252, 0xffffe000, v194
	ds_read_b64_tr_b16 v[70:71], v193 offset:24576
	ds_read_b64_tr_b16 v[72:73], v193 offset:25088
	ds_read_b64_tr_b16 v[98:99], v193 offset:28672
	ds_read_b64_tr_b16 v[100:101], v193 offset:29184
	ds_read_b128 v[66:69], v66
	ds_read_b128 v[236:239], v252 offset:512
	ds_read_b128 v[240:243], v252 offset:2048
	ds_read_b128 v[244:247], v252 offset:2560
	ds_read_b128 v[248:251], v252 offset:4096
	s_waitcnt lgkmcnt(7)
	v_mfma_f32_32x32x16_bf16 v[18:33], v[164:167], v[70:73], v[18:33]
	ds_read_b64_tr_b16 v[102:103], v193 offset:57344
	ds_read_b64_tr_b16 v[104:105], v193 offset:57856
	s_waitcnt lgkmcnt(7)
	v_mfma_f32_32x32x16_bf16 v[50:65], v[164:167], v[98:101], v[50:65]
	ds_read_b64_tr_b16 v[106:107], v193 offset:61440
	ds_read_b64_tr_b16 v[108:109], v193 offset:61952
	s_waitcnt lgkmcnt(2)
	v_mfma_f32_32x32x16_bf16 v[34:49], v[164:167], v[102:105], v[34:49]
	ds_read_b64_tr_b16 v[70:71], v193 offset:25600
	ds_read_b64_tr_b16 v[72:73], v193 offset:26112
	s_waitcnt lgkmcnt(2)
	v_mfma_f32_32x32x16_bf16 v[2:17], v[164:167], v[106:109], v[2:17]
	ds_read_b64_tr_b16 v[180:181], v193 offset:29696
	ds_read_b64_tr_b16 v[182:183], v193 offset:30208
	v_max_f32_e32 v98, v131, v131
	v_max_f32_e32 v99, v130, v130
	v_max_f32_e32 v98, v99, v98
	v_max3_f32 v99, v132, v133, v115
	v_max3_f32 v98, v98, v114, v116
	v_max3_f32 v98, v98, v117, v134
	v_max3_f32 v99, v99, v136, v137
	v_max3_f32 v98, v98, v135, v118
	v_max3_f32 v99, v99, v120, v121
	v_max3_f32 v98, v98, v119, v138
	v_max3_f32 v99, v99, v140, v141
	v_max3_f32 v98, v98, v139, v122
	v_max3_f32 v99, v99, v124, v125
	v_max3_f32 v98, v98, v123, v142
	v_max3_f32 v99, v99, v144, v145
	v_max3_f32 v98, v98, v143, v126
	v_max3_f32 v99, v99, v128, v129
	v_max3_f32 v98, v98, v127, v99
	v_mov_b32_e32 v99, v98
	s_nop 1
	v_permlane32_swap_b32_e32 v98, v99
	v_max_f32_e32 v99, v99, v99
	v_max_f32_e32 v98, v98, v98
	v_max_f32_e32 v98, v98, v99
	v_cmp_lt_f32_e32 vcc, s15, v98
	s_cmp_lg_u64 vcc, 0
	s_cselect_b64 s[4:5], -1, 0
	s_cbranch_vccz .LBB0_806
	v_max_f32_e32 v82, v98, v98
	v_max_f32_e32 v98, 0, v82
	v_exp_f32_e64 v99, -v98
	v_add_f32_e32 v212, v212, v98
	v_xor_b32_e32 v82, 0x80000000, v212
	v_mov_b32_e32 v83, v82
	v_mov_b32_e32 v84, v82
	v_mov_b32_e32 v85, v82
	v_mov_b32_e32 v86, v82
	v_mov_b32_e32 v87, v82
	v_mov_b32_e32 v88, v82
	v_mov_b32_e32 v89, v82
	v_mov_b32_e32 v90, v82
	v_mov_b32_e32 v91, v82
	v_mov_b32_e32 v92, v82
	v_mov_b32_e32 v93, v82
	v_mov_b32_e32 v94, v82
	v_mov_b32_e32 v95, v82
	v_mov_b32_e32 v96, v82
	v_mov_b32_e32 v97, v82
	s_and_saveexec_b64 s[22:23], s[8:9]
	ds_write_b32 v1, v99
	s_or_b64 exec, exec, s[22:23]
	v_sub_f32_e32 v145, v145, v98
	v_sub_f32_e32 v144, v144, v98
	v_sub_f32_e32 v143, v143, v98
	v_sub_f32_e32 v142, v142, v98
	v_sub_f32_e32 v141, v141, v98
	v_sub_f32_e32 v140, v140, v98
	v_sub_f32_e32 v139, v139, v98
	v_sub_f32_e32 v138, v138, v98
	v_sub_f32_e32 v137, v137, v98
	v_sub_f32_e32 v136, v136, v98
	v_sub_f32_e32 v135, v135, v98
	v_sub_f32_e32 v134, v134, v98
	v_sub_f32_e32 v133, v133, v98
	v_sub_f32_e32 v132, v132, v98
	v_sub_f32_e32 v131, v131, v98
	v_sub_f32_e32 v130, v130, v98
	v_sub_f32_e32 v129, v129, v98
	v_sub_f32_e32 v128, v128, v98
	v_sub_f32_e32 v127, v127, v98
	v_sub_f32_e32 v126, v126, v98
	v_sub_f32_e32 v125, v125, v98
	v_sub_f32_e32 v124, v124, v98
	v_sub_f32_e32 v123, v123, v98
	v_sub_f32_e32 v122, v122, v98
	v_sub_f32_e32 v121, v121, v98
	v_sub_f32_e32 v120, v120, v98
	v_sub_f32_e32 v119, v119, v98
	v_sub_f32_e32 v118, v118, v98
	v_sub_f32_e32 v117, v117, v98
	v_sub_f32_e32 v116, v116, v98
	v_sub_f32_e32 v115, v115, v98
	v_sub_f32_e32 v114, v114, v98
	v_mul_f32_e32 v192, v192, v99
.LBB0_806:
	v_cvt_pk_bf16_f32 v176, v74, v75
	v_cvt_pk_bf16_f32 v177, v76, v77
	v_cvt_pk_bf16_f32 v178, v78, v79
	v_cvt_pk_bf16_f32 v179, v80, v81
	v_exp_f32_e32 v164, v130
	v_mfma_f32_32x32x16_bf16 v[98:113], v[66:69], v[148:151], v[82:97]
	v_exp_f32_e32 v165, v131
	v_exp_f32_e32 v195, v132
	ds_read_b64_tr_b16 v[216:217], v193 offset:58368
	ds_read_b64_tr_b16 v[218:219], v193 offset:58880
	v_exp_f32_e32 v213, v133
	v_add_f32_e32 v66, 0, v164
	s_waitcnt lgkmcnt(4)
	v_mfma_f32_32x32x16_bf16 v[18:33], v[168:171], v[70:73], v[18:33]
	v_add_f32_e32 v66, v165, v66
	v_add_f32_e32 v66, v195, v66
	v_add_f32_e32 v228, v213, v66
	ds_read_b64_tr_b16 v[130:131], v193 offset:62464
	ds_read_b64_tr_b16 v[132:133], v193 offset:62976
	v_exp_f32_e32 v229, v134
	v_mfma_f32_32x32x16_bf16 v[66:81], v[236:239], v[148:151], v[82:97]
	ds_read_b128 v[236:239], v252 offset:4608
	v_exp_f32_e32 v220, v135
	v_exp_f32_e32 v221, v136
	v_exp_f32_e32 v222, v137
	v_add_f32_e32 v134, v229, v228
	v_add_f32_e32 v134, v220, v134
	v_add_f32_e32 v134, v221, v134
	v_add_f32_e32 v223, v222, v134
	s_waitcnt lgkmcnt(5)
	v_mfma_f32_32x32x16_bf16 v[50:65], v[168:171], v[180:183], v[50:65]
	v_exp_f32_e32 v228, v138
	v_mfma_f32_32x32x16_bf16 v[98:113], v[240:243], v[152:155], v[98:113]
	ds_read_b128 v[240:243], v252 offset:6144
	v_exp_f32_e32 v230, v139
	v_exp_f32_e32 v224, v140
	ds_read_b64_tr_b16 v[134:135], v193 offset:26624
	ds_read_b64_tr_b16 v[136:137], v193 offset:27136
	v_exp_f32_e32 v225, v141
	v_add_f32_e32 v138, v228, v223
	s_waitcnt lgkmcnt(6)
	v_mfma_f32_32x32x16_bf16 v[34:49], v[168:171], v[216:219], v[34:49]
	v_add_f32_e32 v138, v230, v138
	v_add_f32_e32 v138, v224, v138
	v_add_f32_e32 v223, v225, v138
	v_cvt_pk_bf16_f32 v164, v164, v165
	v_cvt_pk_bf16_f32 v165, v195, v213
	v_exp_f32_e32 v195, v142
	v_mfma_f32_32x32x16_bf16 v[66:81], v[244:247], v[152:155], v[66:81]
	ds_read_b128 v[244:247], v252 offset:6656
	v_exp_f32_e32 v213, v143
	v_exp_f32_e32 v180, v144
	ds_read_b64_tr_b16 v[138:139], v193 offset:30720
	ds_read_b64_tr_b16 v[140:141], v193 offset:31232
	v_exp_f32_e32 v181, v145
	v_add_f32_e32 v142, v195, v223
	s_waitcnt lgkmcnt(7)
	v_mfma_f32_32x32x16_bf16 v[2:17], v[168:171], v[130:133], v[2:17]
	v_add_f32_e32 v142, v213, v142
	v_add_f32_e32 v142, v180, v142
	v_add_f32_e32 v182, v181, v142
	v_cvt_pk_bf16_f32 v166, v229, v220
	v_cvt_pk_bf16_f32 v167, v221, v222
	v_mfma_f32_32x32x16_bf16 v[98:113], v[248:251], v[156:159], v[98:113]
	v_exp_f32_e32 v183, v114
	ds_read_b64_tr_b16 v[130:131], v193 offset:59392
	ds_read_b64_tr_b16 v[132:133], v193 offset:59904
	v_exp_f32_e32 v220, v115
	v_add_f32_e32 v114, v183, v182
	v_cvt_pk_bf16_f32 v168, v228, v230
	s_waitcnt lgkmcnt(5)
	v_mfma_f32_32x32x16_bf16 v[18:33], v[172:175], v[134:137], v[18:33]
	v_add_f32_e32 v114, v220, v114
	v_cvt_pk_bf16_f32 v169, v224, v225
	s_waitcnt lgkmcnt(2)
	v_mfma_f32_32x32x16_bf16 v[50:65], v[172:175], v[138:141], v[50:65]
	v_exp_f32_e32 v182, v116
	ds_read_b64_tr_b16 v[134:135], v193 offset:63488
	ds_read_b64_tr_b16 v[136:137], v193 offset:64000
	v_exp_f32_e32 v216, v117
	v_cvt_pk_bf16_f32 v170, v195, v213
	v_add_f32_e32 v114, v182, v114
	v_cvt_pk_bf16_f32 v171, v180, v181
	v_add_f32_e32 v114, v216, v114
	v_mfma_f32_32x32x16_bf16 v[66:81], v[236:239], v[156:159], v[66:81]
	v_exp_f32_e32 v142, v118
	ds_read_b64_tr_b16 v[138:139], v193 offset:27648
	ds_read_b64_tr_b16 v[140:141], v193 offset:28160
	v_exp_f32_e32 v143, v119
	v_add_f32_e32 v114, v142, v114
	v_add_f32_e32 v114, v143, v114
	s_waitcnt lgkmcnt(4)
	v_mfma_f32_32x32x16_bf16 v[34:49], v[172:175], v[130:133], v[34:49]
	s_waitcnt lgkmcnt(2)
	v_mfma_f32_32x32x16_bf16 v[2:17], v[172:175], v[134:137], v[2:17]
	v_exp_f32_e32 v144, v120
	ds_read_b64_tr_b16 v[130:131], v193 offset:31744
	ds_read_b64_tr_b16 v[132:133], v193 offset:32256
	v_exp_f32_e32 v145, v121
	v_add_f32_e32 v114, v144, v114
	v_add_f32_e32 v172, v145, v114
	v_mfma_f32_32x32x16_bf16 v[98:113], v[240:243], v[160:163], v[98:113]
	v_exp_f32_e32 v114, v122
	ds_read_b64_tr_b16 v[134:135], v193 offset:60416
	ds_read_b64_tr_b16 v[136:137], v193 offset:60928
	v_exp_f32_e32 v115, v123
	v_add_f32_e32 v116, v114, v172
	v_cvt_pk_bf16_f32 v172, v183, v220
	s_waitcnt lgkmcnt(4)
	v_mfma_f32_32x32x16_bf16 v[18:33], v[176:179], v[138:141], v[18:33]
	v_add_f32_e32 v180, v115, v116
	v_cvt_pk_bf16_f32 v173, v182, v216
	s_waitcnt lgkmcnt(2)
	v_mfma_f32_32x32x16_bf16 v[50:65], v[176:179], v[130:133], v[50:65]
	v_exp_f32_e32 v116, v124
	v_exp_f32_e32 v117, v125
	ds_read_b64_tr_b16 v[122:123], v193 offset:64512
	ds_read_b64_tr_b16 v[124:125], v193 offset:65024
	v_cvt_pk_bf16_f32 v174, v142, v143
	v_add_f32_e32 v138, v116, v180
	v_add_f32_e32 v138, v117, v138
	v_cvt_pk_bf16_f32 v175, v144, v145
	v_mfma_f32_32x32x16_bf16 v[66:81], v[244:247], v[160:163], v[66:81]
	v_exp_f32_e32 v118, v126
	v_exp_f32_e32 v119, v127
	v_add_f32_e32 v120, v118, v138
	v_add_f32_e32 v126, v119, v120
	s_waitcnt lgkmcnt(2)
	v_mfma_f32_32x32x16_bf16 v[34:49], v[176:179], v[134:137], v[34:49]
	s_waitcnt lgkmcnt(0)
	v_mfma_f32_32x32x16_bf16 v[2:17], v[176:179], v[122:125], v[2:17]
	v_exp_f32_e32 v120, v128
	v_exp_f32_e32 v121, v129
	v_add_f32_e32 v122, v120, v126
	v_add_f32_e32 v122, v121, v122
	s_andn2_b64 vcc, exec, s[4:5]
	s_cbranch_vccnz .LBB0_808
	s_waitcnt lgkmcnt(0)
	ds_read_b128 v[124:127], v215 offset:96
	ds_read_b128 v[128:131], v215 offset:64
	ds_read_b128 v[132:135], v215
	ds_read_b128 v[136:139], v215 offset:32
	s_waitcnt lgkmcnt(0)
	v_pk_mul_f32 v[32:33], v[32:33], v[126:127]
	v_pk_mul_f32 v[30:31], v[30:31], v[124:125]
	v_pk_mul_f32 v[28:29], v[28:29], v[130:131]
	v_pk_mul_f32 v[26:27], v[26:27], v[128:129]
	v_pk_mul_f32 v[24:25], v[24:25], v[138:139]
	v_pk_mul_f32 v[22:23], v[22:23], v[136:137]
	v_pk_mul_f32 v[20:21], v[20:21], v[134:135]
	v_pk_mul_f32 v[18:19], v[18:19], v[132:133]
	v_pk_mul_f32 v[64:65], v[64:65], v[126:127]
	v_pk_mul_f32 v[62:63], v[62:63], v[124:125]
	v_pk_mul_f32 v[60:61], v[60:61], v[130:131]
	v_pk_mul_f32 v[58:59], v[58:59], v[128:129]
	v_pk_mul_f32 v[56:57], v[56:57], v[138:139]
	v_pk_mul_f32 v[54:55], v[54:55], v[136:137]
	v_pk_mul_f32 v[52:53], v[52:53], v[134:135]
	v_pk_mul_f32 v[50:51], v[50:51], v[132:133]
	v_pk_mul_f32 v[48:49], v[48:49], v[126:127]
	v_pk_mul_f32 v[46:47], v[46:47], v[124:125]
	v_pk_mul_f32 v[44:45], v[44:45], v[130:131]
	v_pk_mul_f32 v[42:43], v[42:43], v[128:129]
	v_pk_mul_f32 v[40:41], v[40:41], v[138:139]
	v_pk_mul_f32 v[38:39], v[38:39], v[136:137]
	v_pk_mul_f32 v[36:37], v[36:37], v[134:135]
	v_pk_mul_f32 v[34:35], v[34:35], v[132:133]
	v_pk_mul_f32 v[16:17], v[16:17], v[126:127]
	v_pk_mul_f32 v[14:15], v[14:15], v[124:125]
	v_pk_mul_f32 v[12:13], v[12:13], v[130:131]
	v_pk_mul_f32 v[10:11], v[10:11], v[128:129]
	v_pk_mul_f32 v[8:9], v[8:9], v[138:139]
	v_pk_mul_f32 v[6:7], v[6:7], v[136:137]
	v_pk_mul_f32 v[4:5], v[4:5], v[134:135]
	v_pk_mul_f32 v[2:3], v[2:3], v[132:133]

.LBB0_857:
	s_mul_hi_u32 s4, s56, 0xaaaaaaab
	s_lshr_b32 s50, s4, 1
	s_mul_i32 s4, s50, 0xffffa000
	s_add_i32 s4, s14, s4
	s_and_b32 s51, s14, 0x6000
	v_add_u32_e32 v216, s4, v187
	v_add_u32_e32 v215, s51, v209
	v_add_u32_e32 v114, 0xffffc000, v216
	v_add_u32_e32 v252, 0xffffc000, v216
	ds_read_b64_tr_b16 v[118:119], v215 offset:24576
	ds_read_b64_tr_b16 v[120:121], v215 offset:25088
	ds_read_b64_tr_b16 v[122:123], v215 offset:28672
	ds_read_b64_tr_b16 v[124:125], v215 offset:29184
	ds_read_b128 v[114:117], v114
	ds_read_b128 v[236:239], v252 offset:512
	ds_read_b128 v[240:243], v252 offset:2048
	ds_read_b128 v[244:247], v252 offset:2560
	ds_read_b128 v[248:251], v252 offset:4096
	s_waitcnt lgkmcnt(7)
	v_mfma_f32_32x32x16_bf16 v[18:33], v[164:167], v[118:121], v[18:33]
	ds_read_b64_tr_b16 v[126:127], v215 offset:57344
	ds_read_b64_tr_b16 v[128:129], v215 offset:57856
	s_waitcnt lgkmcnt(7)
	v_mfma_f32_32x32x16_bf16 v[50:65], v[164:167], v[122:125], v[50:65]
	ds_read_b64_tr_b16 v[130:131], v215 offset:61440
	ds_read_b64_tr_b16 v[132:133], v215 offset:61952
	s_waitcnt lgkmcnt(2)
	v_mfma_f32_32x32x16_bf16 v[34:49], v[164:167], v[126:129], v[34:49]
	ds_read_b64_tr_b16 v[118:119], v215 offset:25600
	ds_read_b64_tr_b16 v[120:121], v215 offset:26112
	s_waitcnt lgkmcnt(2)
	v_mfma_f32_32x32x16_bf16 v[2:17], v[164:167], v[130:133], v[2:17]
	ds_read_b64_tr_b16 v[180:181], v215 offset:29696
	ds_read_b64_tr_b16 v[182:183], v215 offset:30208
	v_max_f32_e32 v122, v99, v99
	v_max_f32_e32 v123, v98, v98
	v_max_f32_e32 v122, v123, v122
	v_max3_f32 v123, v100, v101, v67
	v_max3_f32 v122, v122, v66, v68
	v_max3_f32 v122, v122, v69, v102
	v_max3_f32 v123, v123, v104, v105
	v_max3_f32 v122, v122, v103, v70
	v_max3_f32 v123, v123, v72, v73
	v_max3_f32 v122, v122, v71, v106
	v_max3_f32 v123, v123, v108, v109
	v_max3_f32 v122, v122, v107, v74
	v_max3_f32 v123, v123, v76, v77
	v_max3_f32 v122, v122, v75, v110
	v_max3_f32 v123, v123, v112, v113
	v_max3_f32 v122, v122, v111, v78
	v_max3_f32 v123, v123, v80, v81
	v_max3_f32 v122, v122, v79, v123
	v_mov_b32_e32 v123, v122
	s_nop 1
	v_permlane32_swap_b32_e32 v122, v123
	v_max_f32_e32 v123, v123, v123
	v_max_f32_e32 v122, v122, v122
	v_max_f32_e32 v122, v122, v123
	v_cmp_lt_f32_e32 vcc, s15, v122
	s_cmp_lg_u64 vcc, 0
	s_cselect_b64 s[4:5], -1, 0
	s_cbranch_vccz .LBB0_861
	v_max_f32_e32 v82, v122, v122
	v_max_f32_e32 v122, 0, v82
	v_exp_f32_e64 v123, -v122
	v_add_f32_e32 v210, v210, v122
	v_xor_b32_e32 v82, 0x80000000, v210
	v_mov_b32_e32 v83, v82
	v_mov_b32_e32 v84, v82
	v_mov_b32_e32 v85, v82
	v_mov_b32_e32 v86, v82
	v_mov_b32_e32 v87, v82
	v_mov_b32_e32 v88, v82
	v_mov_b32_e32 v89, v82
	v_mov_b32_e32 v90, v82
	v_mov_b32_e32 v91, v82
	v_mov_b32_e32 v92, v82
	v_mov_b32_e32 v93, v82
	v_mov_b32_e32 v94, v82
	v_mov_b32_e32 v95, v82
	v_mov_b32_e32 v96, v82
	v_mov_b32_e32 v97, v82
	s_and_saveexec_b64 s[82:83], s[6:7]
	ds_write_b32 v147, v123
	s_or_b64 exec, exec, s[82:83]
	v_sub_f32_e32 v113, v113, v122
	v_sub_f32_e32 v112, v112, v122
	v_sub_f32_e32 v111, v111, v122
	v_sub_f32_e32 v110, v110, v122
	v_sub_f32_e32 v109, v109, v122
	v_sub_f32_e32 v108, v108, v122
	v_sub_f32_e32 v107, v107, v122
	v_sub_f32_e32 v106, v106, v122
	v_sub_f32_e32 v105, v105, v122
	v_sub_f32_e32 v104, v104, v122
	v_sub_f32_e32 v103, v103, v122
	v_sub_f32_e32 v102, v102, v122
	v_sub_f32_e32 v101, v101, v122
	v_sub_f32_e32 v100, v100, v122
	v_sub_f32_e32 v99, v99, v122
	v_sub_f32_e32 v98, v98, v122
	v_sub_f32_e32 v81, v81, v122
	v_sub_f32_e32 v80, v80, v122
	v_sub_f32_e32 v79, v79, v122
	v_sub_f32_e32 v78, v78, v122
	v_sub_f32_e32 v77, v77, v122
	v_sub_f32_e32 v76, v76, v122
	v_sub_f32_e32 v75, v75, v122
	v_sub_f32_e32 v74, v74, v122
	v_sub_f32_e32 v73, v73, v122
	v_sub_f32_e32 v72, v72, v122
	v_sub_f32_e32 v71, v71, v122
	v_sub_f32_e32 v70, v70, v122
	v_sub_f32_e32 v69, v69, v122
	v_sub_f32_e32 v68, v68, v122
	v_sub_f32_e32 v67, v67, v122
	v_sub_f32_e32 v66, v66, v122
	v_mul_f32_e32 v213, v213, v123
.LBB0_861:
	v_exp_f32_e32 v164, v98
	v_mfma_f32_32x32x16_bf16 v[130:145], v[114:117], v[148:151], v[82:97]
	v_exp_f32_e32 v165, v99
	v_exp_f32_e32 v217, v100
	ds_read_b64_tr_b16 v[218:219], v215 offset:58368
	ds_read_b64_tr_b16 v[220:221], v215 offset:58880
	v_exp_f32_e32 v230, v101
	v_add_f32_e32 v98, 0, v164
	s_waitcnt lgkmcnt(4)
	v_mfma_f32_32x32x16_bf16 v[18:33], v[168:171], v[118:121], v[18:33]
	v_add_f32_e32 v98, v165, v98
	v_add_f32_e32 v98, v217, v98
	v_add_f32_e32 v231, v230, v98
	ds_read_b64_tr_b16 v[98:99], v215 offset:62464
	ds_read_b64_tr_b16 v[100:101], v215 offset:62976
	v_exp_f32_e32 v232, v102
	v_mfma_f32_32x32x16_bf16 v[114:129], v[236:239], v[148:151], v[82:97]
	ds_read_b128 v[236:239], v252 offset:4608
	v_exp_f32_e32 v222, v103
	v_exp_f32_e32 v223, v104
	v_exp_f32_e32 v224, v105
	v_add_f32_e32 v102, v232, v231
	v_add_f32_e32 v102, v222, v102
	v_add_f32_e32 v102, v223, v102
	v_add_f32_e32 v225, v224, v102
	s_waitcnt lgkmcnt(5)
	v_mfma_f32_32x32x16_bf16 v[50:65], v[168:171], v[180:183], v[50:65]
	v_exp_f32_e32 v231, v106
	v_mfma_f32_32x32x16_bf16 v[130:145], v[240:243], v[152:155], v[130:145]
	ds_read_b128 v[240:243], v252 offset:6144
	v_exp_f32_e32 v233, v107
	v_exp_f32_e32 v226, v108
	ds_read_b64_tr_b16 v[102:103], v215 offset:26624
	ds_read_b64_tr_b16 v[104:105], v215 offset:27136
	v_exp_f32_e32 v227, v109
	v_add_f32_e32 v106, v231, v225
	s_waitcnt lgkmcnt(6)
	v_mfma_f32_32x32x16_bf16 v[34:49], v[168:171], v[218:221], v[34:49]
	v_add_f32_e32 v106, v233, v106
	v_add_f32_e32 v106, v226, v106
	v_add_f32_e32 v225, v227, v106
	v_cvt_pk_bf16_f32 v164, v164, v165
	v_cvt_pk_bf16_f32 v165, v217, v230
	v_exp_f32_e32 v217, v110
	v_mfma_f32_32x32x16_bf16 v[114:129], v[244:247], v[152:155], v[114:129]
	ds_read_b128 v[244:247], v252 offset:6656
	v_exp_f32_e32 v228, v111
	v_exp_f32_e32 v180, v112
	ds_read_b64_tr_b16 v[106:107], v215 offset:30720
	ds_read_b64_tr_b16 v[108:109], v215 offset:31232
	v_exp_f32_e32 v181, v113
	v_add_f32_e32 v110, v217, v225
	s_waitcnt lgkmcnt(7)
	v_mfma_f32_32x32x16_bf16 v[2:17], v[168:171], v[98:101], v[2:17]
	v_add_f32_e32 v110, v228, v110
	v_add_f32_e32 v110, v180, v110
	v_add_f32_e32 v182, v181, v110
	v_cvt_pk_bf16_f32 v166, v232, v222
	v_cvt_pk_bf16_f32 v167, v223, v224
	v_mfma_f32_32x32x16_bf16 v[130:145], v[248:251], v[156:159], v[130:145]
	v_exp_f32_e32 v183, v66
	ds_read_b64_tr_b16 v[98:99], v215 offset:59392
	ds_read_b64_tr_b16 v[100:101], v215 offset:59904
	v_exp_f32_e32 v222, v67
	v_add_f32_e32 v66, v183, v182
	v_cvt_pk_bf16_f32 v168, v231, v233
	s_waitcnt lgkmcnt(5)
	v_mfma_f32_32x32x16_bf16 v[18:33], v[172:175], v[102:105], v[18:33]
	v_add_f32_e32 v66, v222, v66
	v_cvt_pk_bf16_f32 v169, v226, v227
	s_waitcnt lgkmcnt(2)
	v_mfma_f32_32x32x16_bf16 v[50:65], v[172:175], v[106:109], v[50:65]
	v_exp_f32_e32 v182, v68
	ds_read_b64_tr_b16 v[102:103], v215 offset:63488
	ds_read_b64_tr_b16 v[104:105], v215 offset:64000
	v_exp_f32_e32 v218, v69
	v_cvt_pk_bf16_f32 v170, v217, v228
	v_add_f32_e32 v66, v182, v66
	v_cvt_pk_bf16_f32 v171, v180, v181
	v_add_f32_e32 v219, v218, v66
	v_mfma_f32_32x32x16_bf16 v[114:129], v[236:239], v[156:159], v[114:129]
	v_exp_f32_e32 v110, v70
	ds_read_b64_tr_b16 v[66:67], v215 offset:27648
	ds_read_b64_tr_b16 v[68:69], v215 offset:28160
	v_exp_f32_e32 v111, v71
	v_add_f32_e32 v70, v110, v219
	v_add_f32_e32 v70, v111, v70
	s_waitcnt lgkmcnt(4)
	v_mfma_f32_32x32x16_bf16 v[34:49], v[172:175], v[98:101], v[34:49]
	s_waitcnt lgkmcnt(2)
	v_mfma_f32_32x32x16_bf16 v[2:17], v[172:175], v[102:105], v[2:17]
	v_exp_f32_e32 v112, v72
	ds_read_b64_tr_b16 v[98:99], v215 offset:31744
	ds_read_b64_tr_b16 v[100:101], v215 offset:32256
	v_exp_f32_e32 v113, v73
	v_add_f32_e32 v70, v112, v70
	v_add_f32_e32 v172, v113, v70
	v_mfma_f32_32x32x16_bf16 v[130:145], v[240:243], v[160:163], v[130:145]
	v_exp_f32_e32 v74, v74
	ds_read_b64_tr_b16 v[70:71], v215 offset:60416
	ds_read_b64_tr_b16 v[72:73], v215 offset:60928
	v_exp_f32_e32 v75, v75
	v_add_f32_e32 v106, v74, v172
	v_cvt_pk_bf16_f32 v172, v183, v222
	s_waitcnt lgkmcnt(4)
	v_mfma_f32_32x32x16_bf16 v[18:33], v[176:179], v[66:69], v[18:33]
	v_add_f32_e32 v106, v75, v106
	v_cvt_pk_bf16_f32 v173, v182, v218
	s_waitcnt lgkmcnt(2)
	v_mfma_f32_32x32x16_bf16 v[50:65], v[176:179], v[98:101], v[50:65]
	v_exp_f32_e32 v76, v76
	v_exp_f32_e32 v77, v77
	ds_read_b64_tr_b16 v[66:67], v215 offset:64512
	ds_read_b64_tr_b16 v[68:69], v215 offset:65024
	v_cvt_pk_bf16_f32 v174, v110, v111
	v_add_f32_e32 v106, v76, v106
	v_add_f32_e32 v106, v77, v106
	v_cvt_pk_bf16_f32 v175, v112, v113
	v_mfma_f32_32x32x16_bf16 v[114:129], v[244:247], v[160:163], v[114:129]
	v_exp_f32_e32 v78, v78
	v_exp_f32_e32 v79, v79
	v_add_f32_e32 v98, v78, v106
	v_add_f32_e32 v98, v79, v98
	s_waitcnt lgkmcnt(2)
	v_mfma_f32_32x32x16_bf16 v[34:49], v[176:179], v[70:73], v[34:49]
	s_waitcnt lgkmcnt(0)
	v_mfma_f32_32x32x16_bf16 v[2:17], v[176:179], v[66:69], v[2:17]
	v_exp_f32_e32 v80, v80
	v_exp_f32_e32 v81, v81
	v_add_f32_e32 v66, v80, v98
	v_add_f32_e32 v66, v81, v66
	s_andn2_b64 vcc, exec, s[4:5]
	s_cbranch_vccnz .LBB0_863
	s_waitcnt lgkmcnt(0)
	ds_read_b128 v[68:71], v214 offset:96
	ds_read_b128 v[98:101], v214 offset:64
	ds_read_b128 v[102:105], v214 offset:32
	ds_read_b128 v[106:109], v214
	s_waitcnt lgkmcnt(0)
	v_pk_mul_f32 v[30:31], v[30:31], v[68:69]
	v_pk_mul_f32 v[26:27], v[26:27], v[98:99]
	v_pk_mul_f32 v[22:23], v[22:23], v[102:103]
	v_pk_mul_f32 v[32:33], v[32:33], v[70:71]
	v_pk_mul_f32 v[28:29], v[28:29], v[100:101]
	v_pk_mul_f32 v[24:25], v[24:25], v[104:105]
	v_pk_mul_f32 v[20:21], v[20:21], v[108:109]
	v_pk_mul_f32 v[18:19], v[18:19], v[106:107]
	v_pk_mul_f32 v[62:63], v[62:63], v[68:69]
	v_pk_mul_f32 v[58:59], v[58:59], v[98:99]
	v_pk_mul_f32 v[54:55], v[54:55], v[102:103]
	v_pk_mul_f32 v[64:65], v[64:65], v[70:71]
	v_pk_mul_f32 v[60:61], v[60:61], v[100:101]
	v_pk_mul_f32 v[56:57], v[56:57], v[104:105]
	v_pk_mul_f32 v[52:53], v[52:53], v[108:109]
	v_pk_mul_f32 v[50:51], v[50:51], v[106:107]
	v_pk_mul_f32 v[46:47], v[46:47], v[68:69]
	v_pk_mul_f32 v[42:43], v[42:43], v[98:99]
	v_pk_mul_f32 v[38:39], v[38:39], v[102:103]
	v_pk_mul_f32 v[48:49], v[48:49], v[70:71]
	v_pk_mul_f32 v[44:45], v[44:45], v[100:101]
	v_pk_mul_f32 v[40:41], v[40:41], v[104:105]
	v_pk_mul_f32 v[36:37], v[36:37], v[108:109]
	v_pk_mul_f32 v[34:35], v[34:35], v[106:107]
	v_pk_mul_f32 v[14:15], v[14:15], v[68:69]
	v_pk_mul_f32 v[10:11], v[10:11], v[98:99]
	v_pk_mul_f32 v[6:7], v[6:7], v[102:103]
	v_pk_mul_f32 v[16:17], v[16:17], v[70:71]
	v_pk_mul_f32 v[12:13], v[12:13], v[100:101]
	v_pk_mul_f32 v[8:9], v[8:9], v[104:105]
	v_pk_mul_f32 v[4:5], v[4:5], v[108:109]
	v_pk_mul_f32 v[2:3], v[2:3], v[106:107]

.LBB0_870:
	s_mul_hi_u32 s4, s30, 0xaaaaaaab
	s_lshr_b32 s4, s4, 1
	s_mulk_i32 s4, 0xa000
	s_add_i32 s5, s14, 0xffffa000
	s_add_i32 s4, s14, s4
	s_and_b32 s5, s5, 0x6000
	v_add_u32_e32 v194, s4, v187
	v_add_f32_e32 v192, v213, v66
	v_add_u32_e32 v193, s5, v209
	v_add_u32_e32 v66, 0xffffe000, v194
	v_add_u32_e32 v252, 0xffffe000, v194
	ds_read_b64_tr_b16 v[70:71], v193 offset:24576
	ds_read_b64_tr_b16 v[72:73], v193 offset:25088
	ds_read_b64_tr_b16 v[98:99], v193 offset:28672
	ds_read_b64_tr_b16 v[100:101], v193 offset:29184
	ds_read_b128 v[66:69], v66
	ds_read_b128 v[236:239], v252 offset:512
	ds_read_b128 v[240:243], v252 offset:2048
	ds_read_b128 v[244:247], v252 offset:2560
	ds_read_b128 v[248:251], v252 offset:4096
	s_waitcnt lgkmcnt(7)
	v_mfma_f32_32x32x16_bf16 v[18:33], v[164:167], v[70:73], v[18:33]
	ds_read_b64_tr_b16 v[102:103], v193 offset:57344
	ds_read_b64_tr_b16 v[104:105], v193 offset:57856
	s_waitcnt lgkmcnt(7)
	v_mfma_f32_32x32x16_bf16 v[50:65], v[164:167], v[98:101], v[50:65]
	ds_read_b64_tr_b16 v[106:107], v193 offset:61440
	ds_read_b64_tr_b16 v[108:109], v193 offset:61952
	s_waitcnt lgkmcnt(2)
	v_mfma_f32_32x32x16_bf16 v[34:49], v[164:167], v[102:105], v[34:49]
	ds_read_b64_tr_b16 v[70:71], v193 offset:25600
	ds_read_b64_tr_b16 v[72:73], v193 offset:26112
	s_waitcnt lgkmcnt(2)
	v_mfma_f32_32x32x16_bf16 v[2:17], v[164:167], v[106:109], v[2:17]
	ds_read_b64_tr_b16 v[180:181], v193 offset:29696
	ds_read_b64_tr_b16 v[182:183], v193 offset:30208
	v_max_f32_e32 v98, v131, v131
	v_max_f32_e32 v99, v130, v130
	v_max_f32_e32 v98, v99, v98
	v_max3_f32 v99, v132, v133, v115
	v_max3_f32 v98, v98, v114, v116
	v_max3_f32 v98, v98, v117, v134
	v_max3_f32 v99, v99, v136, v137
	v_max3_f32 v98, v98, v135, v118
	v_max3_f32 v99, v99, v120, v121
	v_max3_f32 v98, v98, v119, v138
	v_max3_f32 v99, v99, v140, v141
	v_max3_f32 v98, v98, v139, v122
	v_max3_f32 v99, v99, v124, v125
	v_max3_f32 v98, v98, v123, v142
	v_max3_f32 v99, v99, v144, v145
	v_max3_f32 v98, v98, v143, v126
	v_max3_f32 v99, v99, v128, v129
	v_max3_f32 v98, v98, v127, v99
	v_mov_b32_e32 v99, v98
	s_nop 1
	v_permlane32_swap_b32_e32 v98, v99
	v_max_f32_e32 v99, v99, v99
	v_max_f32_e32 v98, v98, v98
	v_max_f32_e32 v98, v98, v99
	v_cmp_lt_f32_e32 vcc, s15, v98
	s_cmp_lg_u64 vcc, 0
	s_cselect_b64 s[4:5], -1, 0
	s_cbranch_vccz .LBB0_874
	v_max_f32_e32 v82, v98, v98
	v_max_f32_e32 v98, 0, v82
	v_exp_f32_e64 v99, -v98
	v_add_f32_e32 v210, v210, v98
	v_xor_b32_e32 v82, 0x80000000, v210
	v_mov_b32_e32 v83, v82
	v_mov_b32_e32 v84, v82
	v_mov_b32_e32 v85, v82
	v_mov_b32_e32 v86, v82
	v_mov_b32_e32 v87, v82
	v_mov_b32_e32 v88, v82
	v_mov_b32_e32 v89, v82
	v_mov_b32_e32 v90, v82
	v_mov_b32_e32 v91, v82
	v_mov_b32_e32 v92, v82
	v_mov_b32_e32 v93, v82
	v_mov_b32_e32 v94, v82
	v_mov_b32_e32 v95, v82
	v_mov_b32_e32 v96, v82
	v_mov_b32_e32 v97, v82
	s_and_saveexec_b64 s[22:23], s[6:7]
	ds_write_b32 v147, v99
	s_or_b64 exec, exec, s[22:23]
	v_sub_f32_e32 v145, v145, v98
	v_sub_f32_e32 v144, v144, v98
	v_sub_f32_e32 v143, v143, v98
	v_sub_f32_e32 v142, v142, v98
	v_sub_f32_e32 v141, v141, v98
	v_sub_f32_e32 v140, v140, v98
	v_sub_f32_e32 v139, v139, v98
	v_sub_f32_e32 v138, v138, v98
	v_sub_f32_e32 v137, v137, v98
	v_sub_f32_e32 v136, v136, v98
	v_sub_f32_e32 v135, v135, v98
	v_sub_f32_e32 v134, v134, v98
	v_sub_f32_e32 v133, v133, v98
	v_sub_f32_e32 v132, v132, v98
	v_sub_f32_e32 v131, v131, v98
	v_sub_f32_e32 v130, v130, v98
	v_sub_f32_e32 v129, v129, v98
	v_sub_f32_e32 v128, v128, v98
	v_sub_f32_e32 v127, v127, v98
	v_sub_f32_e32 v126, v126, v98
	v_sub_f32_e32 v125, v125, v98
	v_sub_f32_e32 v124, v124, v98
	v_sub_f32_e32 v123, v123, v98
	v_sub_f32_e32 v122, v122, v98
	v_sub_f32_e32 v121, v121, v98
	v_sub_f32_e32 v120, v120, v98
	v_sub_f32_e32 v119, v119, v98
	v_sub_f32_e32 v118, v118, v98
	v_sub_f32_e32 v117, v117, v98
	v_sub_f32_e32 v116, v116, v98
	v_sub_f32_e32 v115, v115, v98
	v_sub_f32_e32 v114, v114, v98
	v_mul_f32_e32 v192, v192, v99
.LBB0_874:
	v_cvt_pk_bf16_f32 v176, v74, v75
	v_cvt_pk_bf16_f32 v177, v76, v77
	v_cvt_pk_bf16_f32 v178, v78, v79
	v_cvt_pk_bf16_f32 v179, v80, v81
	v_exp_f32_e32 v164, v130
	v_mfma_f32_32x32x16_bf16 v[98:113], v[66:69], v[148:151], v[82:97]
	v_exp_f32_e32 v165, v131
	v_exp_f32_e32 v195, v132
	ds_read_b64_tr_b16 v[216:217], v193 offset:58368
	ds_read_b64_tr_b16 v[218:219], v193 offset:58880
	v_exp_f32_e32 v213, v133
	v_add_f32_e32 v66, 0, v164
	s_waitcnt lgkmcnt(4)
	v_mfma_f32_32x32x16_bf16 v[18:33], v[168:171], v[70:73], v[18:33]
	v_add_f32_e32 v66, v165, v66
	v_add_f32_e32 v66, v195, v66
	v_add_f32_e32 v215, v213, v66
	ds_read_b64_tr_b16 v[130:131], v193 offset:62464
	ds_read_b64_tr_b16 v[132:133], v193 offset:62976
	v_exp_f32_e32 v228, v134
	v_mfma_f32_32x32x16_bf16 v[66:81], v[236:239], v[148:151], v[82:97]
	ds_read_b128 v[236:239], v252 offset:4608
	v_exp_f32_e32 v220, v135
	v_exp_f32_e32 v221, v136
	v_exp_f32_e32 v222, v137
	v_add_f32_e32 v134, v228, v215
	v_add_f32_e32 v134, v220, v134
	v_add_f32_e32 v134, v221, v134
	v_add_f32_e32 v215, v222, v134
	s_waitcnt lgkmcnt(5)
	v_mfma_f32_32x32x16_bf16 v[50:65], v[168:171], v[180:183], v[50:65]
	v_exp_f32_e32 v223, v138
	v_mfma_f32_32x32x16_bf16 v[98:113], v[240:243], v[152:155], v[98:113]
	ds_read_b128 v[240:243], v252 offset:6144
	v_exp_f32_e32 v229, v139
	v_exp_f32_e32 v224, v140
	ds_read_b64_tr_b16 v[134:135], v193 offset:26624
	ds_read_b64_tr_b16 v[136:137], v193 offset:27136
	v_exp_f32_e32 v225, v141
	v_add_f32_e32 v138, v223, v215
	s_waitcnt lgkmcnt(6)
	v_mfma_f32_32x32x16_bf16 v[34:49], v[168:171], v[216:219], v[34:49]
	v_add_f32_e32 v138, v229, v138
	v_add_f32_e32 v138, v224, v138
	v_add_f32_e32 v215, v225, v138
	v_cvt_pk_bf16_f32 v164, v164, v165
	v_cvt_pk_bf16_f32 v165, v195, v213
	v_exp_f32_e32 v195, v142
	v_mfma_f32_32x32x16_bf16 v[66:81], v[244:247], v[152:155], v[66:81]
	ds_read_b128 v[244:247], v252 offset:6656
	v_exp_f32_e32 v213, v143
	v_exp_f32_e32 v180, v144
	ds_read_b64_tr_b16 v[138:139], v193 offset:30720
	ds_read_b64_tr_b16 v[140:141], v193 offset:31232
	v_exp_f32_e32 v181, v145
	v_add_f32_e32 v142, v195, v215
	s_waitcnt lgkmcnt(7)
	v_mfma_f32_32x32x16_bf16 v[2:17], v[168:171], v[130:133], v[2:17]
	v_add_f32_e32 v142, v213, v142
	v_add_f32_e32 v142, v180, v142
	v_add_f32_e32 v182, v181, v142
	v_cvt_pk_bf16_f32 v166, v228, v220
	v_cvt_pk_bf16_f32 v167, v221, v222
	v_mfma_f32_32x32x16_bf16 v[98:113], v[248:251], v[156:159], v[98:113]
	v_exp_f32_e32 v183, v114
	ds_read_b64_tr_b16 v[130:131], v193 offset:59392
	ds_read_b64_tr_b16 v[132:133], v193 offset:59904
	v_exp_f32_e32 v215, v115
	v_add_f32_e32 v114, v183, v182
	v_cvt_pk_bf16_f32 v168, v223, v229
	s_waitcnt lgkmcnt(5)
	v_mfma_f32_32x32x16_bf16 v[18:33], v[172:175], v[134:137], v[18:33]
	v_add_f32_e32 v114, v215, v114
	v_cvt_pk_bf16_f32 v169, v224, v225
	s_waitcnt lgkmcnt(2)
	v_mfma_f32_32x32x16_bf16 v[50:65], v[172:175], v[138:141], v[50:65]
	v_exp_f32_e32 v182, v116
	ds_read_b64_tr_b16 v[134:135], v193 offset:63488
	ds_read_b64_tr_b16 v[136:137], v193 offset:64000
	v_exp_f32_e32 v216, v117
	v_cvt_pk_bf16_f32 v170, v195, v213
	v_add_f32_e32 v114, v182, v114
	v_cvt_pk_bf16_f32 v171, v180, v181
	v_add_f32_e32 v114, v216, v114
	v_mfma_f32_32x32x16_bf16 v[66:81], v[236:239], v[156:159], v[66:81]
	v_exp_f32_e32 v142, v118
	ds_read_b64_tr_b16 v[138:139], v193 offset:27648
	ds_read_b64_tr_b16 v[140:141], v193 offset:28160
	v_exp_f32_e32 v143, v119
	v_add_f32_e32 v114, v142, v114
	v_add_f32_e32 v114, v143, v114
	s_waitcnt lgkmcnt(4)
	v_mfma_f32_32x32x16_bf16 v[34:49], v[172:175], v[130:133], v[34:49]
	s_waitcnt lgkmcnt(2)
	v_mfma_f32_32x32x16_bf16 v[2:17], v[172:175], v[134:137], v[2:17]
	v_exp_f32_e32 v144, v120
	ds_read_b64_tr_b16 v[130:131], v193 offset:31744
	ds_read_b64_tr_b16 v[132:133], v193 offset:32256
	v_exp_f32_e32 v145, v121
	v_add_f32_e32 v114, v144, v114
	v_add_f32_e32 v172, v145, v114
	v_mfma_f32_32x32x16_bf16 v[98:113], v[240:243], v[160:163], v[98:113]
	v_exp_f32_e32 v114, v122
	ds_read_b64_tr_b16 v[134:135], v193 offset:60416
	ds_read_b64_tr_b16 v[136:137], v193 offset:60928
	v_exp_f32_e32 v115, v123
	v_add_f32_e32 v116, v114, v172
	v_cvt_pk_bf16_f32 v172, v183, v215
	s_waitcnt lgkmcnt(4)
	v_mfma_f32_32x32x16_bf16 v[18:33], v[176:179], v[138:141], v[18:33]
	v_add_f32_e32 v180, v115, v116
	v_cvt_pk_bf16_f32 v173, v182, v216
	s_waitcnt lgkmcnt(2)
	v_mfma_f32_32x32x16_bf16 v[50:65], v[176:179], v[130:133], v[50:65]
	v_exp_f32_e32 v116, v124
	v_exp_f32_e32 v117, v125
	ds_read_b64_tr_b16 v[122:123], v193 offset:64512
	ds_read_b64_tr_b16 v[124:125], v193 offset:65024
	v_cvt_pk_bf16_f32 v174, v142, v143
	v_add_f32_e32 v138, v116, v180
	v_add_f32_e32 v138, v117, v138
	v_cvt_pk_bf16_f32 v175, v144, v145
	v_mfma_f32_32x32x16_bf16 v[66:81], v[244:247], v[160:163], v[66:81]
	v_exp_f32_e32 v118, v126
	v_exp_f32_e32 v119, v127
	v_add_f32_e32 v120, v118, v138
	v_add_f32_e32 v126, v119, v120
	s_waitcnt lgkmcnt(2)
	v_mfma_f32_32x32x16_bf16 v[34:49], v[176:179], v[134:137], v[34:49]
	s_waitcnt lgkmcnt(0)
	v_mfma_f32_32x32x16_bf16 v[2:17], v[176:179], v[122:125], v[2:17]
	v_exp_f32_e32 v120, v128
	v_exp_f32_e32 v121, v129
	v_add_f32_e32 v122, v120, v126
	v_add_f32_e32 v122, v121, v122
	s_andn2_b64 vcc, exec, s[4:5]
	s_cbranch_vccnz .LBB0_876
	s_waitcnt lgkmcnt(0)
	ds_read_b128 v[124:127], v214 offset:96
	ds_read_b128 v[128:131], v214 offset:64
	ds_read_b128 v[132:135], v214
	ds_read_b128 v[136:139], v214 offset:32
	s_waitcnt lgkmcnt(0)
	v_pk_mul_f32 v[32:33], v[32:33], v[126:127]
	v_pk_mul_f32 v[30:31], v[30:31], v[124:125]
	v_pk_mul_f32 v[28:29], v[28:29], v[130:131]
	v_pk_mul_f32 v[26:27], v[26:27], v[128:129]
	v_pk_mul_f32 v[24:25], v[24:25], v[138:139]
	v_pk_mul_f32 v[22:23], v[22:23], v[136:137]
	v_pk_mul_f32 v[20:21], v[20:21], v[134:135]
	v_pk_mul_f32 v[18:19], v[18:19], v[132:133]
	v_pk_mul_f32 v[64:65], v[64:65], v[126:127]
	v_pk_mul_f32 v[62:63], v[62:63], v[124:125]
	v_pk_mul_f32 v[60:61], v[60:61], v[130:131]
	v_pk_mul_f32 v[58:59], v[58:59], v[128:129]
	v_pk_mul_f32 v[56:57], v[56:57], v[138:139]
	v_pk_mul_f32 v[54:55], v[54:55], v[136:137]
	v_pk_mul_f32 v[52:53], v[52:53], v[134:135]
	v_pk_mul_f32 v[50:51], v[50:51], v[132:133]
	v_pk_mul_f32 v[48:49], v[48:49], v[126:127]
	v_pk_mul_f32 v[46:47], v[46:47], v[124:125]
	v_pk_mul_f32 v[44:45], v[44:45], v[130:131]
	v_pk_mul_f32 v[42:43], v[42:43], v[128:129]
	v_pk_mul_f32 v[40:41], v[40:41], v[138:139]
	v_pk_mul_f32 v[38:39], v[38:39], v[136:137]
	v_pk_mul_f32 v[36:37], v[36:37], v[134:135]
	v_pk_mul_f32 v[34:35], v[34:35], v[132:133]
	v_pk_mul_f32 v[16:17], v[16:17], v[126:127]
	v_pk_mul_f32 v[14:15], v[14:15], v[124:125]
	v_pk_mul_f32 v[12:13], v[12:13], v[130:131]
	v_pk_mul_f32 v[10:11], v[10:11], v[128:129]
	v_pk_mul_f32 v[8:9], v[8:9], v[138:139]
	v_pk_mul_f32 v[6:7], v[6:7], v[136:137]
	v_pk_mul_f32 v[4:5], v[4:5], v[134:135]
	v_pk_mul_f32 v[2:3], v[2:3], v[132:133]
